# NSA compression MLP first GEMM rewritten: A fragments built once per k-step and shared through LDS, W1 rows loaded coalesced and staged in per-wave LDS, next group's loads issued behind the barrier
# speedup vs baseline: 1.0271x; 1.0176x over previous
.LBB0_1780:
	v_readfirstlane_b32 s100, v39
	v_readfirstlane_b32 s20, v30
	v_readfirstlane_b32 s21, v31
	s_lshr_b32 s101, s100, 2
	s_sub_u32 s20, s20, 0x80
	s_subb_u32 s21, s21, 0
	v_lshlrev_b32_e32 v0, 4, v34
	s_lshl_b32 vcc_lo, s100, 10
	s_add_i32 vcc_lo, vcc_lo, 0x8000
	v_add_u32_e32 v164, vcc_lo, v0
	v_add_u32_e32 v165, 0x8000, v0
	s_mul_i32 vcc_lo, s100, 0x2200
	s_add_i32 vcc_lo, vcc_lo, 0xc000
	v_lshrrev_b32_e32 v18, 4, v34
	v_and_b32_e32 v19, 15, v34
	v_mul_u32_u24_e32 v20, 0x110, v18
	v_lshl_add_u32 v20, v19, 4, v20
	v_add_u32_e32 v166, vcc_lo, v20
	v_mul_u32_u24_e32 v20, 0x110, v38
	v_lshl_add_u32 v20, v36, 4, v20
	v_add_u32_e32 v167, vcc_lo, v20
	v_lshlrev_b32_e32 v20, 12, v18
	v_lshl_add_u32 v20, v19, 4, v20
	v_mov_b32_e32 v168, v20
	v_add_u32_e32 v169, 0x4000, v20
	v_add_u32_e32 v170, 0x8000, v20
	v_add_u32_e32 v171, 0xc000, v20
	v_add_u32_e32 v176, 0x10000, v20
	v_add_u32_e32 v177, 0x14000, v20
	v_add_u32_e32 v178, 0x18000, v20
	v_add_u32_e32 v179, 0x1c000, v20
	s_and_b32 vcc_lo, s100, 3
	s_lshl_b32 vcc_lo, vcc_lo, 5
	v_mov_b32_e32 v0, vcc_lo
	v_lshl_add_u64 v[180:181], v[28:29], 0, v[0:1]
	s_lshl_b32 vcc_lo, s100, 6
	v_mov_b32_e32 v0, vcc_lo
	v_lshl_add_u64 v[182:183], v[32:33], 0, v[0:1]
	s_mov_b32 vcc_lo, 16
	v_add_u32_e32 v0, s101, v40
	v_min_u32_e32 v0, 0x1fff, v0
	v_mul_u32_u24_e32 v0, 0xb00, v0
	v_lshlrev_b32_e32 v0, 1, v0
	v_lshl_add_u64 v[20:21], v[180:181], 0, v[0:1]
	global_load_dwordx4 v[52:55], v[20:21], off
	v_lshl_add_u64 v[18:19], v[182:183], 0, s[6:7]
	global_load_dwordx4 v[56:59], v[18:19], off
	global_load_dwordx4 v[60:63], v[18:19], off offset:16
	global_load_dwordx4 v[68:71], v168, s[20:21]
	global_load_dwordx4 v[72:75], v169, s[20:21]
	global_load_dwordx4 v[76:79], v170, s[20:21]
	global_load_dwordx4 v[80:83], v171, s[20:21]
	global_load_dwordx4 v[84:87], v176, s[20:21]
	global_load_dwordx4 v[88:91], v177, s[20:21]
	global_load_dwordx4 v[92:95], v178, s[20:21]
	global_load_dwordx4 v[96:99], v179, s[20:21]
	s_add_u32 s6, s6, 0x200
	s_addc_u32 s7, s7, 0
	v_add_u32_e32 v40, 2, v40
	s_add_u32 s20, s20, 0x100
	s_addc_u32 s21, s21, 0
.Lcp_loop:
	s_waitcnt vmcnt(8)
	v_lshlrev_b32_e32 v64, 16, v52
	v_and_b32_e32 v65, 0xffff0000, v52
	v_pk_add_f32 v[56:57], v[56:57], v[64:65]
	v_lshlrev_b32_e32 v66, 16, v53
	v_and_b32_e32 v67, 0xffff0000, v53
	v_pk_add_f32 v[58:59], v[58:59], v[66:67]
	v_lshlrev_b32_e32 v64, 16, v54
	v_and_b32_e32 v65, 0xffff0000, v54
	v_pk_add_f32 v[60:61], v[60:61], v[64:65]
	v_lshlrev_b32_e32 v66, 16, v55
	v_and_b32_e32 v67, 0xffff0000, v55
	v_pk_add_f32 v[62:63], v[62:63], v[66:67]
	v_cvt_pk_bf16_f32 v52, v56, v57
	v_cvt_pk_bf16_f32 v53, v58, v59
	v_cvt_pk_bf16_f32 v54, v60, v61
	v_cvt_pk_bf16_f32 v55, v62, v63
	ds_write_b128 v164, v[52:55]
	s_waitcnt vmcnt(7)
	ds_write_b128 v166, v[68:71]
	s_waitcnt vmcnt(6)
	ds_write_b128 v166, v[72:75] offset:1088
	s_waitcnt vmcnt(5)
	ds_write_b128 v166, v[76:79] offset:2176
	s_waitcnt vmcnt(4)
	ds_write_b128 v166, v[80:83] offset:3264
	s_waitcnt vmcnt(3)
	ds_write_b128 v166, v[84:87] offset:4352
	s_waitcnt vmcnt(2)
	ds_write_b128 v166, v[88:91] offset:5440
	s_waitcnt vmcnt(1)
	ds_write_b128 v166, v[92:95] offset:6528
	s_waitcnt vmcnt(0)
	ds_write_b128 v166, v[96:99] offset:7616
	s_waitcnt lgkmcnt(0)
	s_barrier
	s_cmpk_eq_i32 s6, 0x2000
	s_cbranch_scc1 .Lcp_noload0
	v_add_u32_e32 v0, s101, v40
	v_min_u32_e32 v0, 0x1fff, v0
	v_mul_u32_u24_e32 v0, 0xb00, v0
	v_lshlrev_b32_e32 v0, 1, v0
	v_lshl_add_u64 v[20:21], v[180:181], 0, v[0:1]
	global_load_dwordx4 v[52:55], v[20:21], off
	v_lshl_add_u64 v[18:19], v[182:183], 0, s[6:7]
	global_load_dwordx4 v[56:59], v[18:19], off
	global_load_dwordx4 v[60:63], v[18:19], off offset:16
	global_load_dwordx4 v[68:71], v168, s[20:21]
	global_load_dwordx4 v[72:75], v169, s[20:21]
	global_load_dwordx4 v[76:79], v170, s[20:21]
	global_load_dwordx4 v[80:83], v171, s[20:21]
	global_load_dwordx4 v[84:87], v176, s[20:21]
	global_load_dwordx4 v[88:91], v177, s[20:21]
	global_load_dwordx4 v[92:95], v178, s[20:21]
	global_load_dwordx4 v[96:99], v179, s[20:21]
	s_add_u32 s6, s6, 0x200
	s_addc_u32 s7, s7, 0
	v_add_u32_e32 v40, 2, v40
	s_add_u32 s20, s20, 0x100
	s_addc_u32 s21, s21, 0
.Lcp_noload0:
	ds_read_b128 v[100:103], v165
	ds_read_b128 v[132:135], v167
	ds_read_b128 v[104:107], v165 offset:1024
	ds_read_b128 v[136:139], v167 offset:32
	ds_read_b128 v[108:111], v165 offset:2048
	ds_read_b128 v[140:143], v167 offset:64
	ds_read_b128 v[112:115], v165 offset:3072
	ds_read_b128 v[144:147], v167 offset:96
	ds_read_b128 v[116:119], v165 offset:4096
	ds_read_b128 v[148:151], v167 offset:128
	ds_read_b128 v[120:123], v165 offset:5120
	ds_read_b128 v[152:155], v167 offset:160
	ds_read_b128 v[124:127], v165 offset:6144
	ds_read_b128 v[156:159], v167 offset:192
	s_waitcnt lgkmcnt(12)
	v_mfma_f32_32x32x16_bf16 v[2:17], v[100:103], v[132:135], v[2:17]
	ds_read_b128 v[128:131], v165 offset:7168
	ds_read_b128 v[160:163], v167 offset:224
	s_waitcnt lgkmcnt(12)
	v_mfma_f32_32x32x16_bf16 v[2:17], v[104:107], v[136:139], v[2:17]
	s_waitcnt lgkmcnt(10)
	v_mfma_f32_32x32x16_bf16 v[2:17], v[108:111], v[140:143], v[2:17]
	s_waitcnt lgkmcnt(8)
	v_mfma_f32_32x32x16_bf16 v[2:17], v[112:115], v[144:147], v[2:17]
	s_waitcnt lgkmcnt(6)
	v_mfma_f32_32x32x16_bf16 v[2:17], v[116:119], v[148:151], v[2:17]
	s_waitcnt lgkmcnt(4)
	v_mfma_f32_32x32x16_bf16 v[2:17], v[120:123], v[152:155], v[2:17]
	s_waitcnt lgkmcnt(2)
	v_mfma_f32_32x32x16_bf16 v[2:17], v[124:127], v[156:159], v[2:17]
	s_waitcnt lgkmcnt(0)
	v_mfma_f32_32x32x16_bf16 v[2:17], v[128:131], v[160:163], v[2:17]
	s_sub_i32 vcc_lo, vcc_lo, 1
	s_waitcnt vmcnt(8)
	v_lshlrev_b32_e32 v64, 16, v52
	v_and_b32_e32 v65, 0xffff0000, v52
	v_pk_add_f32 v[56:57], v[56:57], v[64:65]
	v_lshlrev_b32_e32 v66, 16, v53
	v_and_b32_e32 v67, 0xffff0000, v53
	v_pk_add_f32 v[58:59], v[58:59], v[66:67]
	v_lshlrev_b32_e32 v64, 16, v54
	v_and_b32_e32 v65, 0xffff0000, v54
	v_pk_add_f32 v[60:61], v[60:61], v[64:65]
	v_lshlrev_b32_e32 v66, 16, v55
	v_and_b32_e32 v67, 0xffff0000, v55
	v_pk_add_f32 v[62:63], v[62:63], v[66:67]
	v_cvt_pk_bf16_f32 v52, v56, v57
	v_cvt_pk_bf16_f32 v53, v58, v59
	v_cvt_pk_bf16_f32 v54, v60, v61
	v_cvt_pk_bf16_f32 v55, v62, v63
	ds_write_b128 v164, v[52:55] offset:8192
	s_waitcnt vmcnt(7)
	ds_write_b128 v166, v[68:71]
	s_waitcnt vmcnt(6)
	ds_write_b128 v166, v[72:75] offset:1088
	s_waitcnt vmcnt(5)
	ds_write_b128 v166, v[76:79] offset:2176
	s_waitcnt vmcnt(4)
	ds_write_b128 v166, v[80:83] offset:3264
	s_waitcnt vmcnt(3)
	ds_write_b128 v166, v[84:87] offset:4352
	s_waitcnt vmcnt(2)
	ds_write_b128 v166, v[88:91] offset:5440
	s_waitcnt vmcnt(1)
	ds_write_b128 v166, v[92:95] offset:6528
	s_waitcnt vmcnt(0)
	ds_write_b128 v166, v[96:99] offset:7616
	s_waitcnt lgkmcnt(0)
	s_barrier
	s_cmpk_eq_i32 s6, 0x2000
	s_cbranch_scc1 .Lcp_noload1
	v_add_u32_e32 v0, s101, v40
	v_min_u32_e32 v0, 0x1fff, v0
	v_mul_u32_u24_e32 v0, 0xb00, v0
	v_lshlrev_b32_e32 v0, 1, v0
	v_lshl_add_u64 v[20:21], v[180:181], 0, v[0:1]
	global_load_dwordx4 v[52:55], v[20:21], off
	v_lshl_add_u64 v[18:19], v[182:183], 0, s[6:7]
	global_load_dwordx4 v[56:59], v[18:19], off
	global_load_dwordx4 v[60:63], v[18:19], off offset:16
	global_load_dwordx4 v[68:71], v168, s[20:21]
	global_load_dwordx4 v[72:75], v169, s[20:21]
	global_load_dwordx4 v[76:79], v170, s[20:21]
	global_load_dwordx4 v[80:83], v171, s[20:21]
	global_load_dwordx4 v[84:87], v176, s[20:21]
	global_load_dwordx4 v[88:91], v177, s[20:21]
	global_load_dwordx4 v[92:95], v178, s[20:21]
	global_load_dwordx4 v[96:99], v179, s[20:21]
	s_add_u32 s6, s6, 0x200
	s_addc_u32 s7, s7, 0
	v_add_u32_e32 v40, 2, v40
	s_add_u32 s20, s20, 0x100
	s_addc_u32 s21, s21, 0
.Lcp_noload1:
	ds_read_b128 v[100:103], v165 offset:8192
	ds_read_b128 v[132:135], v167
	ds_read_b128 v[104:107], v165 offset:9216
	ds_read_b128 v[136:139], v167 offset:32
	ds_read_b128 v[108:111], v165 offset:10240
	ds_read_b128 v[140:143], v167 offset:64
	ds_read_b128 v[112:115], v165 offset:11264
	ds_read_b128 v[144:147], v167 offset:96
	ds_read_b128 v[116:119], v165 offset:12288
	ds_read_b128 v[148:151], v167 offset:128
	ds_read_b128 v[120:123], v165 offset:13312
	ds_read_b128 v[152:155], v167 offset:160
	ds_read_b128 v[124:127], v165 offset:14336
	ds_read_b128 v[156:159], v167 offset:192
	s_waitcnt lgkmcnt(12)
	v_mfma_f32_32x32x16_bf16 v[2:17], v[100:103], v[132:135], v[2:17]
	ds_read_b128 v[128:131], v165 offset:15360
	ds_read_b128 v[160:163], v167 offset:224
	s_waitcnt lgkmcnt(12)
	v_mfma_f32_32x32x16_bf16 v[2:17], v[104:107], v[136:139], v[2:17]
	s_waitcnt lgkmcnt(10)
	v_mfma_f32_32x32x16_bf16 v[2:17], v[108:111], v[140:143], v[2:17]
	s_waitcnt lgkmcnt(8)
	v_mfma_f32_32x32x16_bf16 v[2:17], v[112:115], v[144:147], v[2:17]
	s_waitcnt lgkmcnt(6)
	v_mfma_f32_32x32x16_bf16 v[2:17], v[116:119], v[148:151], v[2:17]
	s_waitcnt lgkmcnt(4)
	v_mfma_f32_32x32x16_bf16 v[2:17], v[120:123], v[152:155], v[2:17]
	s_waitcnt lgkmcnt(2)
	v_mfma_f32_32x32x16_bf16 v[2:17], v[124:127], v[156:159], v[2:17]
	s_waitcnt lgkmcnt(0)
	v_mfma_f32_32x32x16_bf16 v[2:17], v[128:131], v[160:163], v[2:17]
	s_sub_i32 vcc_lo, vcc_lo, 1
	s_cmp_lg_u32 vcc_lo, 0
	s_cbranch_scc1 .Lcp_loop
	s_lshl_b32 s6, s94, 8
	s_mov_b32 s7, s95
	s_lshl_b64 s[6:7], s[6:7], 2
	s_add_u32 s6, s18, s6
	s_addc_u32 s7, s19, s7
	v_lshl_add_u64 v[18:19], v[26:27], 2, s[6:7]
	global_load_dword v0, v[18:19], off
	v_lshl_add_u32 v18, v26, 1, 0
	s_movk_i32 s6, 0x840
	v_lshl_or_b32 v30, v36, 2, 1
	v_cmp_gt_i32_e32 vcc, 2, v39
	s_waitcnt vmcnt(0)
	v_add_f32_e32 v2, v2, v0
	v_mul_f32_e32 v19, 0x3d372713, v2
	v_mul_f32_e32 v19, v2, v19
	v_fma_f32 v19, v2, v19, v2
	v_mul_f32_e32 v19, 0x3f4c422a, v19
	v_mul_f32_e32 v19, 0xc038aa3b, v19
	v_exp_f32_e32 v19, v19
	s_nop 0
	v_add_f32_e32 v19, 1.0, v19
	v_rcp_f32_e32 v19, v19
	s_nop 0
	v_mul_f32_e32 v2, v2, v19
	v_cvt_pk_bf16_f32 v2, v2, s0
	v_mad_u32_u24 v19, v36, s6, v18
	ds_write_b16 v19, v2
	v_add_f32_e32 v2, v3, v0
	v_mul_f32_e32 v3, 0x3d372713, v2
	v_mul_f32_e32 v3, v2, v3
	v_fma_f32 v3, v2, v3, v2
	v_mul_f32_e32 v3, 0x3f4c422a, v3
	v_mul_f32_e32 v3, 0xc038aa3b, v3
	v_exp_f32_e32 v3, v3
	s_movk_i32 s6, 0x210
	v_add_f32_e32 v3, 1.0, v3
	v_rcp_f32_e32 v3, v3
	s_nop 0
	v_mul_f32_e32 v2, v2, v3
	v_cvt_pk_bf16_f32 v3, v2, s0
	v_mad_u32_u24 v2, v30, s6, v18
	ds_write_b16 v2, v3
	v_add_f32_e32 v3, v4, v0
	v_mul_f32_e32 v4, 0x3d372713, v3
	v_mul_f32_e32 v4, v3, v4
	v_fma_f32 v4, v3, v4, v3
	v_mul_f32_e32 v4, 0x3f4c422a, v4
	v_mul_f32_e32 v4, 0xc038aa3b, v4
	v_exp_f32_e32 v4, v4
	s_nop 0
	v_add_f32_e32 v4, 1.0, v4
	v_rcp_f32_e32 v4, v4
	s_nop 0
	v_mul_f32_e32 v3, v3, v4
	v_cvt_pk_bf16_f32 v3, v3, s0
	ds_write_b16 v2, v3 offset:528
	v_add_f32_e32 v3, v5, v0
	v_mul_f32_e32 v4, 0x3d372713, v3
	v_mul_f32_e32 v4, v3, v4
	v_fma_f32 v4, v3, v4, v3
	v_mul_f32_e32 v4, 0x3f4c422a, v4
	v_mul_f32_e32 v4, 0xc038aa3b, v4
	v_exp_f32_e32 v4, v4
	s_nop 0
	v_add_f32_e32 v4, 1.0, v4
	v_rcp_f32_e32 v4, v4
	s_nop 0
	v_mul_f32_e32 v3, v3, v4
	v_cvt_pk_bf16_f32 v3, v3, s0
	ds_write_b16 v2, v3 offset:1056
	v_add_f32_e32 v3, v6, v0
	v_mul_f32_e32 v4, 0x3d372713, v3
	v_mul_f32_e32 v4, v3, v4
	v_fma_f32 v4, v3, v4, v3
	v_mul_f32_e32 v4, 0x3f4c422a, v4
	v_mul_f32_e32 v4, 0xc038aa3b, v4
	v_exp_f32_e32 v4, v4
	s_nop 0
	v_add_f32_e32 v4, 1.0, v4
	v_rcp_f32_e32 v4, v4
	s_nop 0
	v_mul_f32_e32 v3, v3, v4
	v_cvt_pk_bf16_f32 v3, v3, s0
	ds_write_b16 v2, v3 offset:3696
	v_add_f32_e32 v3, v7, v0
	v_mul_f32_e32 v4, 0x3d372713, v3
	v_mul_f32_e32 v4, v3, v4
	v_fma_f32 v4, v3, v4, v3
	v_mul_f32_e32 v4, 0x3f4c422a, v4
	v_mul_f32_e32 v4, 0xc038aa3b, v4
	v_exp_f32_e32 v4, v4
	s_nop 0
	v_add_f32_e32 v4, 1.0, v4
	v_rcp_f32_e32 v4, v4
	s_nop 0
	v_mul_f32_e32 v3, v3, v4
	v_cvt_pk_bf16_f32 v3, v3, s0
	ds_write_b16 v2, v3 offset:4224
	v_add_f32_e32 v3, v8, v0
	v_mul_f32_e32 v4, 0x3d372713, v3
	v_mul_f32_e32 v4, v3, v4
	v_fma_f32 v4, v3, v4, v3
	v_mul_f32_e32 v4, 0x3f4c422a, v4
	v_mul_f32_e32 v4, 0xc038aa3b, v4
	v_exp_f32_e32 v4, v4
	s_nop 0
	v_add_f32_e32 v4, 1.0, v4
	v_rcp_f32_e32 v4, v4
	s_nop 0
	v_mul_f32_e32 v3, v3, v4
	v_cvt_pk_bf16_f32 v3, v3, s0
	ds_write_b16 v2, v3 offset:4752
	v_add_f32_e32 v3, v9, v0
	v_mul_f32_e32 v4, 0x3d372713, v3
	v_mul_f32_e32 v4, v3, v4
	v_fma_f32 v4, v3, v4, v3
	v_mul_f32_e32 v4, 0x3f4c422a, v4
	v_mul_f32_e32 v4, 0xc038aa3b, v4
	v_exp_f32_e32 v4, v4
	s_nop 0
	v_add_f32_e32 v4, 1.0, v4
	v_rcp_f32_e32 v4, v4
	s_nop 0
	v_mul_f32_e32 v3, v3, v4
	v_cvt_pk_bf16_f32 v3, v3, s0
	ds_write_b16 v2, v3 offset:5280
	v_add_f32_e32 v3, v10, v0
	v_mul_f32_e32 v4, 0x3d372713, v3
	v_mul_f32_e32 v4, v3, v4
	v_fma_f32 v4, v3, v4, v3
	v_mul_f32_e32 v4, 0x3f4c422a, v4
	v_mul_f32_e32 v4, 0xc038aa3b, v4
	v_exp_f32_e32 v4, v4
	s_nop 0
	v_add_f32_e32 v4, 1.0, v4
	v_rcp_f32_e32 v4, v4
	s_nop 0
	v_mul_f32_e32 v3, v3, v4
	v_cvt_pk_bf16_f32 v3, v3, s0
	ds_write_b16 v2, v3 offset:7920
	v_add_f32_e32 v3, v11, v0
	v_mul_f32_e32 v4, 0x3d372713, v3
	v_mul_f32_e32 v4, v3, v4
	v_fma_f32 v4, v3, v4, v3
	v_mul_f32_e32 v4, 0x3f4c422a, v4
	v_mul_f32_e32 v4, 0xc038aa3b, v4
	v_exp_f32_e32 v4, v4
	s_nop 0
	v_add_f32_e32 v4, 1.0, v4
	v_rcp_f32_e32 v4, v4
	s_nop 0
	v_mul_f32_e32 v3, v3, v4
	v_cvt_pk_bf16_f32 v3, v3, s0
	ds_write_b16 v2, v3 offset:8448
	v_add_f32_e32 v3, v12, v0
	v_mul_f32_e32 v4, 0x3d372713, v3
	v_mul_f32_e32 v4, v3, v4
	v_fma_f32 v4, v3, v4, v3
	v_mul_f32_e32 v4, 0x3f4c422a, v4
	v_mul_f32_e32 v4, 0xc038aa3b, v4
	v_exp_f32_e32 v4, v4
	s_nop 0
	v_add_f32_e32 v4, 1.0, v4
	v_rcp_f32_e32 v4, v4
	s_nop 0
	v_mul_f32_e32 v3, v3, v4
	v_cvt_pk_bf16_f32 v3, v3, s0
	ds_write_b16 v2, v3 offset:8976
	v_add_f32_e32 v3, v13, v0
	v_mul_f32_e32 v4, 0x3d372713, v3
	v_mul_f32_e32 v4, v3, v4
	v_fma_f32 v4, v3, v4, v3
	v_mul_f32_e32 v4, 0x3f4c422a, v4
	v_mul_f32_e32 v4, 0xc038aa3b, v4
	v_exp_f32_e32 v4, v4
	s_nop 0
	v_add_f32_e32 v4, 1.0, v4
	v_rcp_f32_e32 v4, v4
	s_nop 0
	v_mul_f32_e32 v3, v3, v4
	v_cvt_pk_bf16_f32 v3, v3, s0
	ds_write_b16 v2, v3 offset:9504
	v_add_f32_e32 v3, v14, v0
	v_mul_f32_e32 v4, 0x3d372713, v3
	v_mul_f32_e32 v4, v3, v4
	v_fma_f32 v4, v3, v4, v3
	v_mul_f32_e32 v4, 0x3f4c422a, v4
	v_mul_f32_e32 v4, 0xc038aa3b, v4
	v_exp_f32_e32 v4, v4
	s_nop 0
	v_add_f32_e32 v4, 1.0, v4
	v_rcp_f32_e32 v4, v4
	s_nop 0
	v_mul_f32_e32 v3, v3, v4
	v_cvt_pk_bf16_f32 v3, v3, s0
	ds_write_b16 v2, v3 offset:12144
	v_add_f32_e32 v3, v15, v0
	v_mul_f32_e32 v4, 0x3d372713, v3
	v_mul_f32_e32 v4, v3, v4
	v_fma_f32 v4, v3, v4, v3
	v_mul_f32_e32 v4, 0x3f4c422a, v4
	v_mul_f32_e32 v4, 0xc038aa3b, v4
	v_exp_f32_e32 v4, v4
	s_nop 0
	v_add_f32_e32 v4, 1.0, v4
	v_rcp_f32_e32 v4, v4
	s_nop 0
	v_mul_f32_e32 v3, v3, v4
	v_cvt_pk_bf16_f32 v3, v3, s0
	ds_write_b16 v2, v3 offset:12672
	v_add_f32_e32 v3, v16, v0
	v_mul_f32_e32 v4, 0x3d372713, v3
	v_mul_f32_e32 v4, v3, v4
	v_fma_f32 v4, v3, v4, v3
	v_mul_f32_e32 v4, 0x3f4c422a, v4
	v_mul_f32_e32 v4, 0xc038aa3b, v4
	v_exp_f32_e32 v4, v4
	v_add_f32_e32 v0, v17, v0
	v_add_f32_e32 v4, 1.0, v4
	v_rcp_f32_e32 v4, v4
	s_nop 0
	v_mul_f32_e32 v3, v3, v4
	v_cvt_pk_bf16_f32 v3, v3, s0
	ds_write_b16 v2, v3 offset:13200
	v_mul_f32_e32 v3, 0x3d372713, v0
	v_mul_f32_e32 v3, v0, v3
	v_fma_f32 v3, v0, v3, v0
	v_mul_f32_e32 v3, 0x3f4c422a, v3
	v_mul_f32_e32 v3, 0xc038aa3b, v3
	v_exp_f32_e32 v3, v3
	s_nop 0
	v_add_f32_e32 v3, 1.0, v3
	v_rcp_f32_e32 v3, v3
	s_nop 0
	v_mul_f32_e32 v0, v0, v3
	v_cvt_pk_bf16_f32 v0, v0, s0
	ds_write_b16 v2, v0 offset:13728
	s_waitcnt lgkmcnt(0)
	s_barrier
	s_and_saveexec_b64 s[6:7], vcc
	s_mov_b32 s28, 0x40c00000
	s_cbranch_execz .LBB0_1783
	s_lshl_b64 s[18:19], s[94:95], 16
	s_add_u32 s18, s8, s18
	s_addc_u32 s19, s9, s19
	s_lshl_b32 s94, s94, 6
	s_lshl_b64 s[8:9], s[94:95], 2
	s_add_u32 s8, s16, s8
	s_movk_i32 s16, 0x210
	v_mad_u32_u24 v31, v38, s16, 0
	v_lshlrev_b64 v[22:23], 2, v[26:27]
	v_lshl_add_u32 v0, v36, 4, v31
	v_lshl_add_u64 v[24:25], s[18:19], 0, v[22:23]
	ds_read_b128 v[2:5], v0
	v_lshlrev_b32_e32 v0, 11, v36
	v_lshl_add_u64 v[28:29], v[24:25], 0, v[0:1]
	global_load_dword v0, v[28:29], off
	global_load_dword v6, v[28:29], off offset:256
	global_load_dword v7, v[28:29], off offset:512
	global_load_dword v8, v[28:29], off offset:768
	global_load_dword v9, v[28:29], off offset:1024
	global_load_dword v10, v[28:29], off offset:1280
	global_load_dword v11, v[28:29], off offset:1536
	global_load_dword v12, v[28:29], off offset:1792
	s_movk_i32 s16, 0x1000
	s_addc_u32 s9, s17, s9
	s_waitcnt vmcnt(6)
	v_cvt_pk_bf16_f32 v6, v0, v6
	v_or_b32_e32 v0, 16, v37
	v_lshl_add_u32 v18, v0, 1, v31
	v_lshlrev_b32_e32 v0, 8, v0
	v_lshl_add_u64 v[32:33], v[24:25], 0, v[0:1]
	global_load_dword v0, v[32:33], off
	v_add_co_u32_e32 v32, vcc, s16, v28
	ds_read_b128 v[18:21], v18
	s_nop 0
	v_addc_co_u32_e32 v33, vcc, 0, v29, vcc
	global_load_dword v27, v[32:33], off offset:256
	global_load_dword v39, v[32:33], off offset:512
	global_load_dword v40, v[32:33], off offset:768
	global_load_dword v41, v[32:33], off offset:1024
	global_load_dword v42, v[32:33], off offset:1280
	global_load_dword v43, v[32:33], off offset:1536
	s_nop 0
	global_load_dword v32, v[32:33], off offset:1792
	s_waitcnt vmcnt(12)
	v_cvt_pk_bf16_f32 v7, v7, v8
	s_waitcnt vmcnt(10)
	v_cvt_pk_bf16_f32 v8, v9, v10
	s_waitcnt vmcnt(8)
	v_cvt_pk_bf16_f32 v9, v11, v12
	s_movk_i32 s16, 0x3000
	s_waitcnt vmcnt(6)
	v_cvt_pk_bf16_f32 v38, v0, v27
	s_waitcnt lgkmcnt(1)
	v_mfma_f32_32x32x16_bf16 v[2:17], v[2:5], v[6:9], 0
	s_waitcnt vmcnt(4)
	v_cvt_pk_bf16_f32 v39, v39, v40
	v_or_b32_e32 v0, 32, v37
	s_waitcnt vmcnt(2)
	v_cvt_pk_bf16_f32 v40, v41, v42
	s_waitcnt vmcnt(0)
	v_cvt_pk_bf16_f32 v41, v43, v32
	s_waitcnt lgkmcnt(0)
	s_nop 0
	v_mfma_f32_32x32x16_bf16 v[2:17], v[18:21], v[38:41], v[2:17]
	v_lshl_add_u32 v18, v0, 1, v31
	v_lshlrev_b32_e32 v0, 8, v0
	v_lshl_add_u64 v[32:33], v[24:25], 0, v[0:1]
	global_load_dword v0, v[32:33], off
	v_add_co_u32_e32 v32, vcc, s25, v28
	ds_read_b128 v[18:21], v18
	s_nop 0
	v_addc_co_u32_e32 v33, vcc, 0, v29, vcc
	global_load_dword v27, v[32:33], off offset:256
	global_load_dword v39, v[32:33], off offset:512
	global_load_dword v40, v[32:33], off offset:768
	global_load_dword v41, v[32:33], off offset:1024
	global_load_dword v42, v[32:33], off offset:1280
	global_load_dword v43, v[32:33], off offset:1536
	s_nop 0
	global_load_dword v32, v[32:33], off offset:1792
	s_waitcnt vmcnt(6)
	v_cvt_pk_bf16_f32 v38, v0, v27
	v_or_b32_e32 v0, 48, v37
	s_waitcnt vmcnt(4)
	v_cvt_pk_bf16_f32 v39, v39, v40
	s_waitcnt vmcnt(2)
	v_cvt_pk_bf16_f32 v40, v41, v42
	s_waitcnt vmcnt(0)
	v_cvt_pk_bf16_f32 v41, v43, v32
	s_waitcnt lgkmcnt(0)
	s_nop 0
	v_mfma_f32_32x32x16_bf16 v[2:17], v[18:21], v[38:41], v[2:17]
	v_lshl_add_u32 v18, v0, 1, v31
	v_lshlrev_b32_e32 v0, 8, v0
	v_lshl_add_u64 v[32:33], v[24:25], 0, v[0:1]
	global_load_dword v0, v[32:33], off
	v_add_co_u32_e32 v32, vcc, s16, v28
	ds_read_b128 v[18:21], v18
	s_nop 0
	v_addc_co_u32_e32 v33, vcc, 0, v29, vcc
	global_load_dword v27, v[32:33], off offset:256
	global_load_dword v39, v[32:33], off offset:512
	global_load_dword v40, v[32:33], off offset:768
	global_load_dword v41, v[32:33], off offset:1024
	global_load_dword v42, v[32:33], off offset:1280
	global_load_dword v43, v[32:33], off offset:1536
	s_nop 0
	global_load_dword v32, v[32:33], off offset:1792
	s_movk_i32 s16, 0x4000
	s_waitcnt vmcnt(6)
	v_cvt_pk_bf16_f32 v38, v0, v27
	v_or_b32_e32 v0, 64, v37
	s_waitcnt vmcnt(4)
	v_cvt_pk_bf16_f32 v39, v39, v40
	s_waitcnt vmcnt(2)
	v_cvt_pk_bf16_f32 v40, v41, v42
	s_waitcnt vmcnt(0)
	v_cvt_pk_bf16_f32 v41, v43, v32
	s_waitcnt lgkmcnt(0)
	s_nop 0
	v_mfma_f32_32x32x16_bf16 v[2:17], v[18:21], v[38:41], v[2:17]
	v_lshl_add_u32 v18, v0, 1, v31
	v_lshlrev_b32_e32 v0, 8, v0
	v_lshl_add_u64 v[32:33], v[24:25], 0, v[0:1]
	global_load_dword v0, v[32:33], off
	v_add_co_u32_e32 v32, vcc, s16, v28
	ds_read_b128 v[18:21], v18
	s_nop 0
	v_addc_co_u32_e32 v33, vcc, 0, v29, vcc
	global_load_dword v27, v[32:33], off offset:256
	global_load_dword v39, v[32:33], off offset:512
	global_load_dword v40, v[32:33], off offset:768
	global_load_dword v41, v[32:33], off offset:1024
	global_load_dword v42, v[32:33], off offset:1280
	global_load_dword v43, v[32:33], off offset:1536
	s_nop 0
	global_load_dword v32, v[32:33], off offset:1792
	s_movk_i32 s16, 0x5000
	s_waitcnt vmcnt(6)
	v_cvt_pk_bf16_f32 v38, v0, v27
	v_or_b32_e32 v0, 0x50, v37
	s_waitcnt vmcnt(4)
	v_cvt_pk_bf16_f32 v39, v39, v40
	s_waitcnt vmcnt(2)
	v_cvt_pk_bf16_f32 v40, v41, v42
	s_waitcnt vmcnt(0)
	v_cvt_pk_bf16_f32 v41, v43, v32
	s_waitcnt lgkmcnt(0)
	s_nop 0
	v_mfma_f32_32x32x16_bf16 v[2:17], v[18:21], v[38:41], v[2:17]
	v_lshl_add_u32 v18, v0, 1, v31
	v_lshlrev_b32_e32 v0, 8, v0
	v_lshl_add_u64 v[32:33], v[24:25], 0, v[0:1]
	global_load_dword v0, v[32:33], off
	v_add_co_u32_e32 v32, vcc, s16, v28
	ds_read_b128 v[18:21], v18
	s_nop 0
	v_addc_co_u32_e32 v33, vcc, 0, v29, vcc
	global_load_dword v27, v[32:33], off offset:256
	global_load_dword v39, v[32:33], off offset:512
	global_load_dword v40, v[32:33], off offset:768
	global_load_dword v41, v[32:33], off offset:1024
	global_load_dword v42, v[32:33], off offset:1280
	global_load_dword v43, v[32:33], off offset:1536
	s_nop 0
	global_load_dword v32, v[32:33], off offset:1792
	s_movk_i32 s16, 0x6000
	s_waitcnt vmcnt(6)
	v_cvt_pk_bf16_f32 v38, v0, v27
	v_or_b32_e32 v0, 0x60, v37
	s_waitcnt vmcnt(4)
	v_cvt_pk_bf16_f32 v39, v39, v40
	s_waitcnt vmcnt(2)
	v_cvt_pk_bf16_f32 v40, v41, v42
	s_waitcnt vmcnt(0)
	v_cvt_pk_bf16_f32 v41, v43, v32
	s_waitcnt lgkmcnt(0)
	s_nop 0
	v_mfma_f32_32x32x16_bf16 v[2:17], v[18:21], v[38:41], v[2:17]
	v_lshl_add_u32 v18, v0, 1, v31
	v_lshlrev_b32_e32 v0, 8, v0
	v_lshl_add_u64 v[32:33], v[24:25], 0, v[0:1]
	global_load_dword v0, v[32:33], off
	v_add_co_u32_e32 v32, vcc, s16, v28
	ds_read_b128 v[18:21], v18
	s_nop 0
	v_addc_co_u32_e32 v33, vcc, 0, v29, vcc
	global_load_dword v27, v[32:33], off offset:256
	global_load_dword v39, v[32:33], off offset:512
	global_load_dword v40, v[32:33], off offset:768
	global_load_dword v41, v[32:33], off offset:1024
	global_load_dword v42, v[32:33], off offset:1280
	global_load_dword v43, v[32:33], off offset:1536
	s_nop 0
	global_load_dword v32, v[32:33], off offset:1792
	s_movk_i32 s16, 0x7000
	s_waitcnt vmcnt(6)
	v_cvt_pk_bf16_f32 v38, v0, v27
	v_or_b32_e32 v0, 0x70, v37
	s_waitcnt vmcnt(4)
	v_cvt_pk_bf16_f32 v39, v39, v40
	s_waitcnt vmcnt(2)
	v_cvt_pk_bf16_f32 v40, v41, v42
	s_waitcnt vmcnt(0)
	v_cvt_pk_bf16_f32 v41, v43, v32
	s_waitcnt lgkmcnt(0)
	s_nop 0
	v_mfma_f32_32x32x16_bf16 v[2:17], v[18:21], v[38:41], v[2:17]
	v_lshl_add_u32 v18, v0, 1, v31
	v_lshlrev_b32_e32 v0, 8, v0
	v_lshl_add_u64 v[32:33], v[24:25], 0, v[0:1]
	global_load_dword v0, v[32:33], off
	v_add_co_u32_e32 v32, vcc, s16, v28
	ds_read_b128 v[18:21], v18
	s_nop 0
	v_addc_co_u32_e32 v33, vcc, 0, v29, vcc
	global_load_dword v27, v[32:33], off offset:256
	global_load_dword v39, v[32:33], off offset:512
	global_load_dword v40, v[32:33], off offset:768
	global_load_dword v41, v[32:33], off offset:1024
	global_load_dword v42, v[32:33], off offset:1280
	global_load_dword v43, v[32:33], off offset:1536
	s_nop 0
	global_load_dword v32, v[32:33], off offset:1792
	s_mov_b32 s16, 0x9000
	s_waitcnt vmcnt(6)
	v_cvt_pk_bf16_f32 v38, v0, v27
	v_or_b32_e32 v0, 0x80, v37
	s_waitcnt vmcnt(4)
	v_cvt_pk_bf16_f32 v39, v39, v40
	s_waitcnt vmcnt(2)
	v_cvt_pk_bf16_f32 v40, v41, v42
	s_waitcnt vmcnt(0)
	v_cvt_pk_bf16_f32 v41, v43, v32
	s_waitcnt lgkmcnt(0)
	s_nop 0
	v_mfma_f32_32x32x16_bf16 v[2:17], v[18:21], v[38:41], v[2:17]
	v_lshl_add_u32 v18, v0, 1, v31
	v_lshlrev_b32_e32 v0, 8, v0
	v_lshl_add_u64 v[32:33], v[24:25], 0, v[0:1]
	global_load_dword v0, v[32:33], off
	v_add_co_u32_e32 v32, vcc, s54, v28
	ds_read_b128 v[18:21], v18
	s_nop 0
	v_addc_co_u32_e32 v33, vcc, 0, v29, vcc
	global_load_dword v27, v[32:33], off offset:256
	global_load_dword v39, v[32:33], off offset:512
	global_load_dword v40, v[32:33], off offset:768
	global_load_dword v41, v[32:33], off offset:1024
	global_load_dword v42, v[32:33], off offset:1280
	global_load_dword v43, v[32:33], off offset:1536
	s_nop 0
	global_load_dword v32, v[32:33], off offset:1792
	s_waitcnt vmcnt(6)
	v_cvt_pk_bf16_f32 v38, v0, v27
	v_or_b32_e32 v0, 0x90, v37
	s_waitcnt vmcnt(4)
	v_cvt_pk_bf16_f32 v39, v39, v40
	s_waitcnt vmcnt(2)
	v_cvt_pk_bf16_f32 v40, v41, v42
	s_waitcnt vmcnt(0)
	v_cvt_pk_bf16_f32 v41, v43, v32
	s_waitcnt lgkmcnt(0)
	s_nop 0
	v_mfma_f32_32x32x16_bf16 v[2:17], v[18:21], v[38:41], v[2:17]
	v_lshl_add_u32 v18, v0, 1, v31
	v_lshlrev_b32_e32 v0, 8, v0
	v_lshl_add_u64 v[32:33], v[24:25], 0, v[0:1]
	global_load_dword v0, v[32:33], off
	v_add_co_u32_e32 v32, vcc, s16, v28
	ds_read_b128 v[18:21], v18
	s_nop 0
	v_addc_co_u32_e32 v33, vcc, 0, v29, vcc
	global_load_dword v27, v[32:33], off offset:256
	global_load_dword v39, v[32:33], off offset:512
	global_load_dword v40, v[32:33], off offset:768
	global_load_dword v41, v[32:33], off offset:1024
	global_load_dword v42, v[32:33], off offset:1280
	global_load_dword v43, v[32:33], off offset:1536
	s_nop 0
	global_load_dword v32, v[32:33], off offset:1792
	s_mov_b32 s16, 0xa000
	s_waitcnt vmcnt(6)
	v_cvt_pk_bf16_f32 v38, v0, v27
	v_or_b32_e32 v0, 0xa0, v37
	s_waitcnt vmcnt(4)
	v_cvt_pk_bf16_f32 v39, v39, v40
	s_waitcnt vmcnt(2)
	v_cvt_pk_bf16_f32 v40, v41, v42
	s_waitcnt vmcnt(0)
	v_cvt_pk_bf16_f32 v41, v43, v32
	s_waitcnt lgkmcnt(0)
	s_nop 0
	v_mfma_f32_32x32x16_bf16 v[2:17], v[18:21], v[38:41], v[2:17]
	v_lshl_add_u32 v18, v0, 1, v31
	v_lshlrev_b32_e32 v0, 8, v0
	v_lshl_add_u64 v[32:33], v[24:25], 0, v[0:1]
	global_load_dword v0, v[32:33], off
	v_add_co_u32_e32 v32, vcc, s16, v28
	ds_read_b128 v[18:21], v18
	s_nop 0
	v_addc_co_u32_e32 v33, vcc, 0, v29, vcc
	global_load_dword v27, v[32:33], off offset:256
	global_load_dword v39, v[32:33], off offset:512
	global_load_dword v40, v[32:33], off offset:768
	global_load_dword v41, v[32:33], off offset:1024
	global_load_dword v42, v[32:33], off offset:1280
	global_load_dword v43, v[32:33], off offset:1536
	s_nop 0
	global_load_dword v32, v[32:33], off offset:1792
	s_mov_b32 s16, 0xb000
	s_waitcnt vmcnt(6)
	v_cvt_pk_bf16_f32 v38, v0, v27
	v_or_b32_e32 v0, 0xb0, v37
	s_waitcnt vmcnt(4)
	v_cvt_pk_bf16_f32 v39, v39, v40
	s_waitcnt vmcnt(2)
	v_cvt_pk_bf16_f32 v40, v41, v42
	s_waitcnt vmcnt(0)
	v_cvt_pk_bf16_f32 v41, v43, v32
	s_waitcnt lgkmcnt(0)
	s_nop 0
	v_mfma_f32_32x32x16_bf16 v[2:17], v[18:21], v[38:41], v[2:17]
	v_lshl_add_u32 v18, v0, 1, v31
	v_lshlrev_b32_e32 v0, 8, v0
	v_lshl_add_u64 v[32:33], v[24:25], 0, v[0:1]
	global_load_dword v0, v[32:33], off
	v_add_co_u32_e32 v32, vcc, s16, v28
	ds_read_b128 v[18:21], v18
	s_nop 0
	v_addc_co_u32_e32 v33, vcc, 0, v29, vcc
	global_load_dword v27, v[32:33], off offset:256
	global_load_dword v39, v[32:33], off offset:512
	global_load_dword v40, v[32:33], off offset:768
	global_load_dword v41, v[32:33], off offset:1024
	global_load_dword v42, v[32:33], off offset:1280
	global_load_dword v43, v[32:33], off offset:1536
	s_nop 0
	global_load_dword v32, v[32:33], off offset:1792
	s_mov_b32 s16, 0xc000
	s_waitcnt vmcnt(6)
	v_cvt_pk_bf16_f32 v38, v0, v27
	v_or_b32_e32 v0, 0xc0, v37
	s_waitcnt vmcnt(4)
	v_cvt_pk_bf16_f32 v39, v39, v40
	s_waitcnt vmcnt(2)
	v_cvt_pk_bf16_f32 v40, v41, v42
	s_waitcnt vmcnt(0)
	v_cvt_pk_bf16_f32 v41, v43, v32
	s_waitcnt lgkmcnt(0)
	s_nop 0
	v_mfma_f32_32x32x16_bf16 v[2:17], v[18:21], v[38:41], v[2:17]
	v_lshl_add_u32 v18, v0, 1, v31
	v_lshlrev_b32_e32 v0, 8, v0
	v_lshl_add_u64 v[32:33], v[24:25], 0, v[0:1]
	global_load_dword v0, v[32:33], off
	v_add_co_u32_e32 v32, vcc, s16, v28
	ds_read_b128 v[18:21], v18
	s_nop 0
	v_addc_co_u32_e32 v33, vcc, 0, v29, vcc
	global_load_dword v27, v[32:33], off offset:256
	global_load_dword v39, v[32:33], off offset:512
	global_load_dword v40, v[32:33], off offset:768
	global_load_dword v41, v[32:33], off offset:1024
	global_load_dword v42, v[32:33], off offset:1280
	global_load_dword v43, v[32:33], off offset:1536
	s_nop 0
	global_load_dword v32, v[32:33], off offset:1792
	s_mov_b32 s16, 0xd000
	s_waitcnt vmcnt(6)
	v_cvt_pk_bf16_f32 v38, v0, v27
	v_or_b32_e32 v0, 0xd0, v37
	s_waitcnt vmcnt(4)
	v_cvt_pk_bf16_f32 v39, v39, v40
	s_waitcnt vmcnt(2)
	v_cvt_pk_bf16_f32 v40, v41, v42
	s_waitcnt vmcnt(0)
	v_cvt_pk_bf16_f32 v41, v43, v32
	s_waitcnt lgkmcnt(0)
	s_nop 0
	v_mfma_f32_32x32x16_bf16 v[2:17], v[18:21], v[38:41], v[2:17]
	v_lshl_add_u32 v18, v0, 1, v31
	v_lshlrev_b32_e32 v0, 8, v0
	v_lshl_add_u64 v[32:33], v[24:25], 0, v[0:1]
	global_load_dword v0, v[32:33], off
	v_add_co_u32_e32 v32, vcc, s16, v28
	ds_read_b128 v[18:21], v18
	s_nop 0
	v_addc_co_u32_e32 v33, vcc, 0, v29, vcc
	global_load_dword v27, v[32:33], off offset:256
	global_load_dword v39, v[32:33], off offset:512
	global_load_dword v40, v[32:33], off offset:768
	global_load_dword v41, v[32:33], off offset:1024
	global_load_dword v42, v[32:33], off offset:1280
	global_load_dword v43, v[32:33], off offset:1536
	s_nop 0
	global_load_dword v32, v[32:33], off offset:1792
	s_mov_b32 s16, 0xe000
	s_waitcnt vmcnt(6)
	v_cvt_pk_bf16_f32 v38, v0, v27
	v_or_b32_e32 v0, 0xe0, v37
	s_waitcnt vmcnt(4)
	v_cvt_pk_bf16_f32 v39, v39, v40
	s_waitcnt vmcnt(2)
	v_cvt_pk_bf16_f32 v40, v41, v42
	s_waitcnt vmcnt(0)
	v_cvt_pk_bf16_f32 v41, v43, v32
	s_waitcnt lgkmcnt(0)
	s_nop 0
	v_mfma_f32_32x32x16_bf16 v[2:17], v[18:21], v[38:41], v[2:17]
	v_lshl_add_u32 v18, v0, 1, v31
	v_lshlrev_b32_e32 v0, 8, v0
	v_lshl_add_u64 v[32:33], v[24:25], 0, v[0:1]
	global_load_dword v0, v[32:33], off
	v_add_co_u32_e32 v32, vcc, s16, v28
	ds_read_b128 v[18:21], v18
	s_nop 0
	v_addc_co_u32_e32 v33, vcc, 0, v29, vcc
	global_load_dword v27, v[32:33], off offset:256
	global_load_dword v39, v[32:33], off offset:512
	global_load_dword v40, v[32:33], off offset:768
	global_load_dword v41, v[32:33], off offset:1024
	global_load_dword v42, v[32:33], off offset:1280
	global_load_dword v43, v[32:33], off offset:1536
	s_nop 0
	global_load_dword v32, v[32:33], off offset:1792
	s_mov_b32 s16, 0xf000
	s_waitcnt vmcnt(6)
	v_cvt_pk_bf16_f32 v38, v0, v27
	v_or_b32_e32 v0, 0xf0, v37
	s_waitcnt vmcnt(4)
	v_cvt_pk_bf16_f32 v39, v39, v40
	s_waitcnt vmcnt(2)
	v_cvt_pk_bf16_f32 v40, v41, v42
	s_waitcnt vmcnt(0)
	v_cvt_pk_bf16_f32 v41, v43, v32
	s_waitcnt lgkmcnt(0)
	s_nop 0
	v_mfma_f32_32x32x16_bf16 v[2:17], v[18:21], v[38:41], v[2:17]
	v_lshl_add_u32 v18, v0, 1, v31
	v_lshlrev_b32_e32 v0, 8, v0
	v_lshl_add_u64 v[24:25], v[24:25], 0, v[0:1]
	global_load_dword v0, v[24:25], off
	v_add_co_u32_e32 v24, vcc, s16, v28
	ds_read_b128 v[18:21], v18
	s_nop 0
	v_addc_co_u32_e32 v25, vcc, 0, v29, vcc
	global_load_dword v27, v[24:25], off offset:256
	global_load_dword v28, v[24:25], off offset:512
	global_load_dword v29, v[24:25], off offset:768
	global_load_dword v31, v[24:25], off offset:1024
	global_load_dword v32, v[24:25], off offset:1280
	global_load_dword v33, v[24:25], off offset:1536
	s_nop 0
	global_load_dword v24, v[24:25], off offset:1792
	s_waitcnt vmcnt(6)
	v_cvt_pk_bf16_f32 v38, v0, v27
	s_waitcnt vmcnt(4)
	v_cvt_pk_bf16_f32 v39, v28, v29
	s_waitcnt vmcnt(2)
	v_cvt_pk_bf16_f32 v40, v31, v32
	s_waitcnt vmcnt(0)
	v_cvt_pk_bf16_f32 v41, v33, v24
	s_waitcnt lgkmcnt(0)
	s_nop 0
	v_mfma_f32_32x32x16_bf16 v[2:17], v[18:21], v[38:41], v[2:17]
	v_lshl_add_u64 v[18:19], s[8:9], 0, v[22:23]
	global_load_dword v0, v[18:19], off
	v_lshl_add_u32 v18, v26, 2, 0
	s_movk_i32 s8, 0x410
	v_mad_u32_u24 v19, v36, s8, v18
	s_movk_i32 s8, 0x104
	s_waitcnt vmcnt(0)
	s_nop 4
	v_add_f32_e32 v2, v0, v2
	ds_write_b32 v19, v2 offset:18432
	v_add_f32_e32 v2, v0, v3
	v_mad_u32_u24 v3, v30, s8, v18
	v_add_f32_e32 v4, v0, v4
	v_add_u32_e32 v18, 0x4800, v3
	ds_write2_b32 v18, v2, v4 offset1:65
	v_add_f32_e32 v2, v0, v5
	ds_write_b32 v3, v2 offset:18952
	v_add_f32_e32 v2, v0, v6
	v_add_f32_e32 v4, v0, v7
	v_add_u32_e32 v5, 0x4e00, v3
	ds_write2_b32 v5, v2, v4 offset0:71 offset1:136
	v_add_f32_e32 v2, v0, v8
	v_add_f32_e32 v4, v0, v9
	v_add_u32_e32 v5, 0x5000, v3
	ds_write2_b32 v5, v2, v4 offset0:73 offset1:138
	v_add_f32_e32 v2, v0, v10
	v_add_f32_e32 v4, v0, v11
	v_add_u32_e32 v5, 0x5600, v3
	ds_write2_b32 v5, v2, v4 offset0:79 offset1:144
	v_add_f32_e32 v2, v0, v12
	v_add_f32_e32 v4, v0, v13
	v_add_u32_e32 v5, 0x5800, v3
	ds_write2_b32 v5, v2, v4 offset0:81 offset1:146
	v_add_f32_e32 v2, v0, v14
	v_add_f32_e32 v4, v0, v15
	v_add_u32_e32 v5, 0x5e00, v3
	ds_write2_b32 v5, v2, v4 offset0:87 offset1:152
	v_add_f32_e32 v2, v0, v16
	v_add_f32_e32 v0, v0, v17
	v_add_u32_e32 v3, 0x6000, v3
	ds_write2_b32 v3, v2, v0 offset0:89 offset1:154

	.amdhsa_kernel _Z8mega_fwd4Args
		.amdhsa_group_segment_fixed_size 0
		.amdhsa_private_segment_fixed_size 0
		.amdhsa_kernarg_size 488
		.amdhsa_user_sgpr_count 2
		.amdhsa_user_sgpr_dispatch_ptr 0
		.amdhsa_user_sgpr_queue_ptr 0
		.amdhsa_user_sgpr_kernarg_segment_ptr 1
		.amdhsa_user_sgpr_dispatch_id 0
		.amdhsa_user_sgpr_kernarg_preload_length 0
		.amdhsa_user_sgpr_kernarg_preload_offset 0
		.amdhsa_user_sgpr_private_segment_size 0
		.amdhsa_uses_dynamic_stack 0
		.amdhsa_enable_private_segment 0
		.amdhsa_system_sgpr_workgroup_id_x 1
		.amdhsa_system_sgpr_workgroup_id_y 0
		.amdhsa_system_sgpr_workgroup_id_z 0
		.amdhsa_system_sgpr_workgroup_info 0
		.amdhsa_system_vgpr_workitem_id 2
		.amdhsa_next_free_vgpr 256
		.amdhsa_next_free_sgpr 102
		.amdhsa_accum_offset 256
		.amdhsa_reserve_vcc 1
		.amdhsa_float_round_mode_32 0
		.amdhsa_float_round_mode_16_64 0
		.amdhsa_float_denorm_mode_32 3
		.amdhsa_float_denorm_mode_16_64 3
		.amdhsa_dx10_clamp 1
		.amdhsa_ieee_mode 1
		.amdhsa_fp16_overflow 0
		.amdhsa_tg_split 0
		.amdhsa_exception_fp_ieee_invalid_op 0
		.amdhsa_exception_fp_denorm_src 0
		.amdhsa_exception_fp_ieee_div_zero 0
		.amdhsa_exception_fp_ieee_overflow 0
		.amdhsa_exception_fp_ieee_underflow 0
		.amdhsa_exception_fp_ieee_inexact 0
		.amdhsa_exception_int_div_zero 0
	.end_amdhsa_kernel
